# merge: sigmoid computed in place and interleaved with the branch-projection MFMAs (separate Q accumulators)
# baseline (speedup 1.0000x reference)
.LBB0_1851:
	s_or_b64 exec, exec, s[0:1]
	v_readlane_b32 s0, v254, 12
	v_readlane_b32 s1, v254, 13
	s_andn2_b64 vcc, exec, s[0:1]
	s_waitcnt lgkmcnt(0)
	s_barrier
	s_cbranch_vccnz .LBB0_1914
	s_getreg_b32 s0, hwreg(HW_REG_HW_ID, 0, 6)
	s_lshl_b32 s0, s0, 2
	s_and_b32 s0, s0, 0xfc
	s_add_i32 s0, s0, 0x24800
	v_mov_b32_e32 v0, s0
	ds_read_b32 v0, v0
	v_mov_b32_e32 v2, 0x244d8
	ds_read2_b32 v[4:5], v2 offset1:1
	ds_read2_b32 v[6:7], v2 offset0:2 offset1:3
	v_mbcnt_lo_u32_b32 v3, -1, 0
	v_mbcnt_hi_u32_b32 v3, -1, v3
	s_waitcnt lgkmcnt(0)
	v_readfirstlane_b32 s38, v0
	v_readfirstlane_b32 s46, v4
	v_readfirstlane_b32 s47, v5
	v_readfirstlane_b32 s2, v6
	v_readfirstlane_b32 s3, v7
	v_readlane_b32 s40, v254, 55
	v_readlane_b32 s41, v254, 56
	v_readlane_b32 s24, v254, 11
	s_lshl_b32 s22, s38, 12
	s_lshl_b32 s25, s38, 11
	s_add_i32 s25, s25, 0x8000
	s_lshr_b32 s0, s38, 1
	s_and_b32 s1, s38, 1
	s_lshl_b32 s39, s0, 13
	s_lshl_b32 s30, s1, 13
	s_add_i32 s30, s30, 0x8000
	v_and_b32_e32 v2, 31, v3
	v_lshrrev_b32_e32 v4, 5, v3
	v_bfe_u32 v5, v3, 1, 3
	v_xor_b32_e32 v5, v5, v4
	v_lshlrev_b32_e32 v6, 7, v2
	v_lshl_or_b32 v7, v5, 4, v6
	v_add_u32_e32 v230, s39, v7
	v_add_u32_e32 v234, s30, v7
	v_xor_b32_e32 v8, 2, v5
	v_lshl_or_b32 v7, v8, 4, v6
	v_add_u32_e32 v231, s39, v7
	v_add_u32_e32 v235, s30, v7
	v_xor_b32_e32 v8, 4, v5
	v_lshl_or_b32 v7, v8, 4, v6
	v_add_u32_e32 v232, s39, v7
	v_add_u32_e32 v237, s30, v7
	v_xor_b32_e32 v8, 6, v5
	v_lshl_or_b32 v7, v8, 4, v6
	v_add_u32_e32 v233, s39, v7
	v_add_u32_e32 v180, s30, v7
	s_lshl_b32 s31, s0, 17
	s_lshl_b32 s0, s1, 7
	s_add_i32 s31, s31, s0
	v_lshlrev_b32_e32 v7, 11, v2
	v_lshl_or_b32 v7, v4, 3, v7
	v_add_u32_e32 v178, s31, v7
	v_add_u32_e32 v179, 0x10000, v178
	v_and_b32_e32 v4, 7, v3
	v_bfe_u32 v5, v3, 4, 2
	v_xor_b32_e32 v4, v4, v5
	v_lshrrev_b32_e32 v5, 3, v3
	v_lshlrev_b32_e32 v6, 11, v5
	v_lshl_or_b32 v6, v4, 4, v6
	v_lshlrev_b32_e32 v7, 9, v5
	v_lshl_or_b32 v7, v4, 4, v7
	s_lshl_b32 s0, s38, 16
	s_add_i32 s1, s0, 0x0
	v_add_u32_e32 v181, s1, v6
	s_add_i32 s1, s0, 0x4000
	v_add_u32_e32 v182, s1, v6
	v_xor_b32_e32 v182, 64, v182
	s_add_i32 s1, s0, 0x8000
	v_add_u32_e32 v183, s1, v6
	s_add_i32 s1, s0, 0xc000
	v_add_u32_e32 v224, s1, v6
	v_xor_b32_e32 v224, 64, v224
	s_lshl_b32 s0, s38, 15
	s_add_i32 s1, s0, 0x0
	v_add_u32_e32 v225, s1, v6
	s_add_i32 s1, s0, 0x4000
	v_add_u32_e32 v226, s1, v6
	v_xor_b32_e32 v226, 64, v226
	s_lshl_b32 s0, s38, 13
	s_add_i32 s1, s0, 0x0
	v_add_u32_e32 v227, s1, v7
	s_add_i32 s1, s0, 0x1000
	v_add_u32_e32 v229, s1, v7
	v_xor_b32_e32 v229, 64, v229
	s_mov_b32 s21, 0
.Lmg_unit:
	s_lshr_b32 s0, s24, 3
	s_and_b32 s1, s24, 7
	s_lshl_b32 s30, s0, 19
	s_add_u32 s4, s46, s30
	s_addc_u32 s5, s47, 0
	s_add_u32 s6, s2, 0x8a00000
	s_addc_u32 s7, s3, 0
	s_add_u32 s6, s6, s30
	s_addc_u32 s7, s7, 0
	s_add_u32 s42, s2, 0xaa00000
	s_addc_u32 s43, s3, 0
	s_add_u32 s42, s42, s30
	s_addc_u32 s43, s43, 0
	s_lshl_b32 s31, s1, 8
	s_add_u32 s42, s42, s31
	s_addc_u32 s43, s43, 0
	s_add_u32 s44, s2, 0x10380000
	s_addc_u32 s45, s3, 0
	s_lshl_b32 s31, s0, 14
	s_add_u32 s44, s44, s31
	s_addc_u32 s45, s45, 0
	s_add_u32 s8, s40, 0x1600000
	s_addc_u32 s9, s41, 0
	s_lshl_b32 s31, s1, 18
	s_add_u32 s8, s8, s31
	s_addc_u32 s9, s9, 0
	s_add_u32 s10, s40, 0x1e00000
	s_addc_u32 s11, s41, 0
	s_lshl_b32 s31, s1, 16
	s_add_u32 s10, s10, s31
	s_addc_u32 s11, s11, 0
	v_mbcnt_lo_u32_b32 v0, -1, 0
	v_mbcnt_hi_u32_b32 v0, -1, v0
	v_and_b32_e32 v0, 31, v0
	v_lshlrev_b32_e32 v0, 6, v0
	s_lshr_b32 s31, s38, 1
	s_lshl_b32 s31, s31, 12
	v_add_u32_e32 v0, s31, v0
	s_waitcnt vmcnt(0)
	global_load_dwordx4 v[2:5], v0, s[44:45] offset:0
	global_load_dwordx4 v[6:9], v0, s[44:45] offset:16
	global_load_dwordx4 v[10:13], v0, s[44:45] offset:32
	global_load_dwordx4 v[14:17], v0, s[44:45] offset:48
	global_load_dwordx4 v[18:21], v0, s[44:45] offset:2048
	global_load_dwordx4 v[22:25], v0, s[44:45] offset:2064
	global_load_dwordx4 v[26:29], v0, s[44:45] offset:2080
	global_load_dwordx4 v[30:33], v0, s[44:45] offset:2096
	v_mov_b32_e32 v66, 0
	v_mov_b32_e32 v67, 0
	v_mov_b32_e32 v68, 0
	v_mov_b32_e32 v69, 0
	v_mov_b32_e32 v70, 0
	v_mov_b32_e32 v71, 0
	v_mov_b32_e32 v72, 0
	v_mov_b32_e32 v73, 0
	v_mov_b32_e32 v74, 0
	v_mov_b32_e32 v75, 0
	v_mov_b32_e32 v76, 0
	v_mov_b32_e32 v77, 0
	v_mov_b32_e32 v78, 0
	v_mov_b32_e32 v79, 0
	v_mov_b32_e32 v80, 0
	v_mov_b32_e32 v81, 0
	v_mov_b32_e32 v82, 0
	v_mov_b32_e32 v83, 0
	v_mov_b32_e32 v84, 0
	v_mov_b32_e32 v85, 0
	v_mov_b32_e32 v86, 0
	v_mov_b32_e32 v87, 0
	v_mov_b32_e32 v88, 0
	v_mov_b32_e32 v89, 0
	v_mov_b32_e32 v90, 0
	v_mov_b32_e32 v91, 0
	v_mov_b32_e32 v92, 0
	v_mov_b32_e32 v93, 0
	v_mov_b32_e32 v94, 0
	v_mov_b32_e32 v95, 0
	v_mov_b32_e32 v96, 0
	v_mov_b32_e32 v97, 0
	v_mov_b32_e32 v98, 0
	v_mov_b32_e32 v99, 0
	v_mov_b32_e32 v100, 0
	v_mov_b32_e32 v101, 0
	v_mov_b32_e32 v102, 0
	v_mov_b32_e32 v103, 0
	v_mov_b32_e32 v104, 0
	v_mov_b32_e32 v105, 0
	v_mov_b32_e32 v106, 0
	v_mov_b32_e32 v107, 0
	v_mov_b32_e32 v108, 0
	v_mov_b32_e32 v109, 0
	v_mov_b32_e32 v110, 0
	v_mov_b32_e32 v111, 0
	v_mov_b32_e32 v112, 0
	v_mov_b32_e32 v113, 0
	v_mov_b32_e32 v114, 0
	v_mov_b32_e32 v115, 0
	v_mov_b32_e32 v116, 0
	v_mov_b32_e32 v117, 0
	v_mov_b32_e32 v118, 0
	v_mov_b32_e32 v119, 0
	v_mov_b32_e32 v120, 0
	v_mov_b32_e32 v121, 0
	v_mov_b32_e32 v122, 0
	v_mov_b32_e32 v123, 0
	v_mov_b32_e32 v124, 0
	v_mov_b32_e32 v125, 0
	v_mov_b32_e32 v126, 0
	v_mov_b32_e32 v127, 0
	v_mov_b32_e32 v128, 0
	v_mov_b32_e32 v129, 0
	s_sub_i32 s23, 0, s21
	v_add_u32_e32 v230, s23, v230
	v_add_u32_e32 v234, s23, v234
	v_add_u32_e32 v231, s23, v231
	v_add_u32_e32 v235, s23, v235
	v_add_u32_e32 v232, s23, v232
	v_add_u32_e32 v237, s23, v237
	v_add_u32_e32 v233, s23, v233
	v_add_u32_e32 v180, s23, v180
	s_mov_b32 s21, 0
	s_waitcnt vmcnt(0)
	v_add_f32_e32 v2, v2, v3
	v_add_f32_e32 v4, v4, v5
	v_add_f32_e32 v6, v6, v7
	v_add_f32_e32 v8, v8, v9
	v_add_f32_e32 v10, v10, v11
	v_add_f32_e32 v12, v12, v13
	v_add_f32_e32 v14, v14, v15
	v_add_f32_e32 v16, v16, v17
	v_add_f32_e32 v2, v2, v4
	v_add_f32_e32 v6, v6, v8
	v_add_f32_e32 v10, v10, v12
	v_add_f32_e32 v14, v14, v16
	v_add_f32_e32 v2, v2, v6
	v_add_f32_e32 v2, v2, v10
	v_add_f32_e32 v2, v2, v14
	v_fmamk_f32 v2, v2, 0x3a800000, v228
	v_rsq_f32_e32 v218, v2
	v_add_f32_e32 v18, v18, v19
	v_add_f32_e32 v20, v20, v21
	v_add_f32_e32 v22, v22, v23
	v_add_f32_e32 v24, v24, v25
	v_add_f32_e32 v26, v26, v27
	v_add_f32_e32 v28, v28, v29
	v_add_f32_e32 v30, v30, v31
	v_add_f32_e32 v32, v32, v33
	v_add_f32_e32 v18, v18, v20
	v_add_f32_e32 v22, v22, v24
	v_add_f32_e32 v26, v26, v28
	v_add_f32_e32 v30, v30, v32
	v_add_f32_e32 v18, v18, v22
	v_add_f32_e32 v18, v18, v26
	v_add_f32_e32 v18, v18, v30
	v_fmamk_f32 v18, v18, 0x3a800000, v228
	v_rsq_f32_e32 v219, v18
	s_add_u32 s12, s4, 0x0
	s_addc_u32 s13, s5, 0
	s_add_u32 s14, s8, 0x0
	s_addc_u32 s15, s9, 0
	s_add_i32 s28, s22, 0x0
	s_add_i32 s29, s25, 0x0
	s_add_i32 m0, s28, 0x0
	s_nop 0
	global_load_lds_dwordx4 v181, s[12:13]
	s_add_i32 m0, s28, 0x400
	s_nop 0
	global_load_lds_dwordx4 v182, s[12:13]
	s_add_i32 m0, s28, 0x800
	s_nop 0
	global_load_lds_dwordx4 v183, s[12:13]
	s_add_i32 m0, s28, 0xc00
	s_nop 0
	global_load_lds_dwordx4 v224, s[12:13]
	s_add_i32 m0, s29, 0x0
	s_nop 0
	global_load_lds_dwordx4 v225, s[14:15]
	s_add_i32 m0, s29, 0x400
	s_nop 0
	global_load_lds_dwordx4 v226, s[14:15]
	s_add_u32 s12, s12, 0x80
	s_addc_u32 s13, s13, 0
	s_add_u32 s14, s14, 0x80
	s_addc_u32 s15, s15, 0
	s_add_i32 s28, s22, 0xc000
	s_add_i32 s29, s25, 0xc000
	s_add_i32 m0, s28, 0x0
	s_nop 0
	global_load_lds_dwordx4 v181, s[12:13]
	s_add_i32 m0, s28, 0x400
	s_nop 0
	global_load_lds_dwordx4 v182, s[12:13]
	s_add_i32 m0, s28, 0x800
	s_nop 0
	global_load_lds_dwordx4 v183, s[12:13]
	s_add_i32 m0, s28, 0xc00
	s_nop 0
	global_load_lds_dwordx4 v224, s[12:13]
	s_add_i32 m0, s29, 0x0
	s_nop 0
	global_load_lds_dwordx4 v225, s[14:15]
	s_add_i32 m0, s29, 0x400
	s_nop 0
	global_load_lds_dwordx4 v226, s[14:15]
	s_add_u32 s12, s12, 0x80
	s_addc_u32 s13, s13, 0
	s_add_u32 s14, s14, 0x80
	s_addc_u32 s15, s15, 0
	s_mov_b32 s20, 0x18000
	s_mov_b32 s26, 0
.Lmg_iloop:
	s_lshl_b32 s30, s26, 21
	s_add_u32 s14, s8, s30
	s_addc_u32 s15, s9, 0
	s_add_u32 s14, s14, 0x100
	s_addc_u32 s15, s15, 0
	s_add_u32 s12, s4, 0x100
	s_addc_u32 s13, s5, 0
	s_lshl_b32 s30, s26, 9
	s_add_u32 s16, s6, s30
	s_addc_u32 s17, s7, 0
	s_lshl_b32 s30, s26, 19
	s_add_u32 s18, s10, s30
	s_addc_u32 s19, s11, 0
	s_add_i32 s30, s26, 1
	s_and_b32 s30, s30, 3
	s_lshl_b32 s30, s30, 21
	s_add_u32 s36, s8, s30
	s_addc_u32 s37, s9, 0
	s_add_u32 s34, s4, 0x0
	s_addc_u32 s35, s5, 0
	s_waitcnt vmcnt(6)
	s_barrier
	ds_read_b128 v[186:189], v234
	ds_read_b128 v[194:197], v230
	ds_read_b128 v[198:201], v230 offset:4096
	ds_read_b128 v[190:193], v234 offset:4096
	s_add_i32 s28, s20, s22
	s_add_i32 s29, s20, s25
	s_add_i32 m0, s28, 0x0
	s_nop 0
	global_load_lds_dwordx4 v181, s[12:13]
	s_add_i32 m0, s28, 0x400
	s_nop 0
	global_load_lds_dwordx4 v182, s[12:13]
	s_add_i32 m0, s28, 0x800
	s_nop 0
	global_load_lds_dwordx4 v183, s[12:13]
	s_add_i32 m0, s28, 0xc00
	s_nop 0
	global_load_lds_dwordx4 v224, s[12:13]
	ds_read_b128 v[162:165], v235
	ds_read_b128 v[170:173], v231
	ds_read_b128 v[174:177], v231 offset:4096
	ds_read_b128 v[166:169], v235 offset:4096
	s_waitcnt lgkmcnt(6)
	s_add_i32 m0, s29, 0x0
	v_mfma_f32_32x32x16_f16 v[2:17], v[186:189], v[194:197], 0
	global_load_lds_dwordx4 v225, s[14:15]
	s_waitcnt lgkmcnt(5)
	s_add_i32 m0, s29, 0x400
	v_mfma_f32_32x32x16_f16 v[18:33], v[186:189], v[198:201], 0
	global_load_lds_dwordx4 v226, s[14:15]
	s_waitcnt lgkmcnt(4)
	v_mfma_f32_32x32x16_f16 v[34:49], v[190:193], v[194:197], 0
	s_add_u32 s12, s12, 0x80
	s_addc_u32 s13, s13, 0
	v_mfma_f32_32x32x16_f16 v[50:65], v[190:193], v[198:201], 0
	s_add_u32 s14, s14, 0x80
	s_addc_u32 s15, s15, 0
	ds_read_b128 v[186:189], v237
	ds_read_b128 v[194:197], v232
	ds_read_b128 v[198:201], v232 offset:4096
	ds_read_b128 v[190:193], v237 offset:4096
	s_add_i32 s20, s20, 0xc000
	s_cmp_eq_u32 s20, 0x24000
	s_cselect_b32 s20, 0, s20
	s_waitcnt lgkmcnt(6)
	v_mfma_f32_32x32x16_f16 v[2:17], v[162:165], v[170:173], v[2:17]
	s_add_i32 s30, s21, 0xc000
	s_waitcnt lgkmcnt(5)
	v_mfma_f32_32x32x16_f16 v[18:33], v[162:165], v[174:177], v[18:33]
	s_cmp_eq_u32 s30, 0x24000
	s_waitcnt lgkmcnt(4)
	v_mfma_f32_32x32x16_f16 v[34:49], v[166:169], v[170:173], v[34:49]
	s_cselect_b32 s30, 0, s30
	v_mfma_f32_32x32x16_f16 v[50:65], v[166:169], v[174:177], v[50:65]
	s_sub_i32 s23, s30, s21
	s_mov_b32 s21, s30
	ds_read_b128 v[162:165], v180
	ds_read_b128 v[170:173], v233
	ds_read_b128 v[174:177], v233 offset:4096
	ds_read_b128 v[166:169], v180 offset:4096
	s_waitcnt lgkmcnt(6)
	v_mfma_f32_32x32x16_f16 v[2:17], v[186:189], v[194:197], v[2:17]
	v_add_u32_e32 v230, s23, v230
	v_add_u32_e32 v234, s23, v234
	s_waitcnt lgkmcnt(5)
	v_mfma_f32_32x32x16_f16 v[18:33], v[186:189], v[198:201], v[18:33]
	v_add_u32_e32 v231, s23, v231
	v_add_u32_e32 v235, s23, v235
	s_waitcnt lgkmcnt(4)
	v_mfma_f32_32x32x16_f16 v[34:49], v[190:193], v[194:197], v[34:49]
	v_add_u32_e32 v232, s23, v232
	v_add_u32_e32 v237, s23, v237
	v_mfma_f32_32x32x16_f16 v[50:65], v[190:193], v[198:201], v[50:65]
	v_add_u32_e32 v233, s23, v233
	v_add_u32_e32 v180, s23, v180
	s_waitcnt lgkmcnt(0)
	s_mov_b32 s27, 13
.Lmg_gloop:
	s_waitcnt vmcnt(6)
	s_barrier
	ds_read_b128 v[186:189], v234
	ds_read_b128 v[194:197], v230
	ds_read_b128 v[198:201], v230 offset:4096
	ds_read_b128 v[190:193], v234 offset:4096
	s_add_i32 s28, s20, s22
	s_add_i32 s29, s20, s25
	s_add_i32 m0, s28, 0x0
	v_mfma_f32_32x32x16_f16 v[2:17], v[162:165], v[170:173], v[2:17]
	global_load_lds_dwordx4 v181, s[12:13]
	s_add_i32 m0, s28, 0x400
	v_mfma_f32_32x32x16_f16 v[18:33], v[162:165], v[174:177], v[18:33]
	global_load_lds_dwordx4 v182, s[12:13]
	s_add_i32 m0, s28, 0x800
	v_mfma_f32_32x32x16_f16 v[34:49], v[166:169], v[170:173], v[34:49]
	global_load_lds_dwordx4 v183, s[12:13]
	s_add_i32 m0, s28, 0xc00
	v_mfma_f32_32x32x16_f16 v[50:65], v[166:169], v[174:177], v[50:65]
	global_load_lds_dwordx4 v224, s[12:13]
	ds_read_b128 v[162:165], v235
	ds_read_b128 v[170:173], v231
	ds_read_b128 v[174:177], v231 offset:4096
	ds_read_b128 v[166:169], v235 offset:4096
	s_waitcnt lgkmcnt(6)
	s_add_i32 m0, s29, 0x0
	v_mfma_f32_32x32x16_f16 v[2:17], v[186:189], v[194:197], v[2:17]
	global_load_lds_dwordx4 v225, s[14:15]
	s_waitcnt lgkmcnt(5)
	s_add_i32 m0, s29, 0x400
	v_mfma_f32_32x32x16_f16 v[18:33], v[186:189], v[198:201], v[18:33]
	global_load_lds_dwordx4 v226, s[14:15]
	s_waitcnt lgkmcnt(4)
	v_mfma_f32_32x32x16_f16 v[34:49], v[190:193], v[194:197], v[34:49]
	s_add_u32 s12, s12, 0x80
	s_addc_u32 s13, s13, 0
	v_mfma_f32_32x32x16_f16 v[50:65], v[190:193], v[198:201], v[50:65]
	s_add_u32 s14, s14, 0x80
	s_addc_u32 s15, s15, 0
	ds_read_b128 v[186:189], v237
	ds_read_b128 v[194:197], v232
	ds_read_b128 v[198:201], v232 offset:4096
	ds_read_b128 v[190:193], v237 offset:4096
	s_add_i32 s20, s20, 0xc000
	s_cmp_eq_u32 s20, 0x24000
	s_cselect_b32 s20, 0, s20
	s_waitcnt lgkmcnt(6)
	v_mfma_f32_32x32x16_f16 v[2:17], v[162:165], v[170:173], v[2:17]
	s_add_i32 s30, s21, 0xc000
	s_waitcnt lgkmcnt(5)
	v_mfma_f32_32x32x16_f16 v[18:33], v[162:165], v[174:177], v[18:33]
	s_cmp_eq_u32 s30, 0x24000
	s_waitcnt lgkmcnt(4)
	v_mfma_f32_32x32x16_f16 v[34:49], v[166:169], v[170:173], v[34:49]
	s_cselect_b32 s30, 0, s30
	v_mfma_f32_32x32x16_f16 v[50:65], v[166:169], v[174:177], v[50:65]
	s_sub_i32 s23, s30, s21
	s_mov_b32 s21, s30
	ds_read_b128 v[162:165], v180
	ds_read_b128 v[170:173], v233
	ds_read_b128 v[174:177], v233 offset:4096
	ds_read_b128 v[166:169], v180 offset:4096
	s_waitcnt lgkmcnt(6)
	v_mfma_f32_32x32x16_f16 v[2:17], v[186:189], v[194:197], v[2:17]
	v_add_u32_e32 v230, s23, v230
	v_add_u32_e32 v234, s23, v234
	s_waitcnt lgkmcnt(5)
	v_mfma_f32_32x32x16_f16 v[18:33], v[186:189], v[198:201], v[18:33]
	v_add_u32_e32 v231, s23, v231
	v_add_u32_e32 v235, s23, v235
	s_waitcnt lgkmcnt(4)
	v_mfma_f32_32x32x16_f16 v[34:49], v[190:193], v[194:197], v[34:49]
	v_add_u32_e32 v232, s23, v232
	v_add_u32_e32 v237, s23, v237
	v_mfma_f32_32x32x16_f16 v[50:65], v[190:193], v[198:201], v[50:65]
	v_add_u32_e32 v233, s23, v233
	v_add_u32_e32 v180, s23, v180
	s_waitcnt lgkmcnt(0)
	s_sub_i32 s27, s27, 1
	s_cmp_lg_u32 s27, 0
	s_cbranch_scc1 .Lmg_gloop
	s_waitcnt vmcnt(6)
	s_barrier
	ds_read_b128 v[186:189], v234
	ds_read_b128 v[194:197], v230
	ds_read_b128 v[198:201], v230 offset:4096
	ds_read_b128 v[190:193], v234 offset:4096
	s_add_i32 s28, s20, s22
	s_add_i32 s29, s20, s25
	s_add_i32 m0, s28, 0x0
	v_mfma_f32_32x32x16_f16 v[2:17], v[162:165], v[170:173], v[2:17]
	global_load_lds_dwordx4 v181, s[16:17]
	s_add_i32 m0, s28, 0x400
	v_mfma_f32_32x32x16_f16 v[18:33], v[162:165], v[174:177], v[18:33]
	global_load_lds_dwordx4 v182, s[16:17]
	s_add_i32 m0, s28, 0x800
	v_mfma_f32_32x32x16_f16 v[34:49], v[166:169], v[170:173], v[34:49]
	global_load_lds_dwordx4 v183, s[16:17]
	s_add_i32 m0, s28, 0xc00
	v_mfma_f32_32x32x16_f16 v[50:65], v[166:169], v[174:177], v[50:65]
	global_load_lds_dwordx4 v224, s[16:17]
	ds_read_b128 v[162:165], v235
	ds_read_b128 v[170:173], v231
	ds_read_b128 v[174:177], v231 offset:4096
	ds_read_b128 v[166:169], v235 offset:4096
	s_waitcnt lgkmcnt(6)
	s_add_i32 m0, s29, 0x0
	v_mfma_f32_32x32x16_f16 v[2:17], v[186:189], v[194:197], v[2:17]
	global_load_lds_dwordx4 v227, s[18:19]
	s_waitcnt lgkmcnt(5)
	s_add_i32 m0, s29, 0x400
	v_mfma_f32_32x32x16_f16 v[18:33], v[186:189], v[198:201], v[18:33]
	global_load_lds_dwordx4 v229, s[18:19]
	s_waitcnt lgkmcnt(4)
	v_mfma_f32_32x32x16_f16 v[34:49], v[190:193], v[194:197], v[34:49]
	s_add_u32 s16, s16, 0x80
	s_addc_u32 s17, s17, 0
	v_mfma_f32_32x32x16_f16 v[50:65], v[190:193], v[198:201], v[50:65]
	s_add_u32 s18, s18, 0x80
	s_addc_u32 s19, s19, 0
	ds_read_b128 v[186:189], v237
	ds_read_b128 v[194:197], v232
	ds_read_b128 v[198:201], v232 offset:4096
	ds_read_b128 v[190:193], v237 offset:4096
	s_add_i32 s20, s20, 0xc000
	s_cmp_eq_u32 s20, 0x24000
	s_cselect_b32 s20, 0, s20
	s_waitcnt lgkmcnt(6)
	v_mfma_f32_32x32x16_f16 v[2:17], v[162:165], v[170:173], v[2:17]
	s_add_i32 s30, s21, 0xc000
	s_waitcnt lgkmcnt(5)
	v_mfma_f32_32x32x16_f16 v[18:33], v[162:165], v[174:177], v[18:33]
	s_cmp_eq_u32 s30, 0x24000
	s_waitcnt lgkmcnt(4)
	v_mfma_f32_32x32x16_f16 v[34:49], v[166:169], v[170:173], v[34:49]
	s_cselect_b32 s30, 0, s30
	v_mfma_f32_32x32x16_f16 v[50:65], v[166:169], v[174:177], v[50:65]
	s_sub_i32 s23, s30, s21
	s_mov_b32 s21, s30
	ds_read_b128 v[162:165], v180
	ds_read_b128 v[170:173], v233
	ds_read_b128 v[174:177], v233 offset:4096
	ds_read_b128 v[166:169], v180 offset:4096
	s_waitcnt lgkmcnt(6)
	v_mfma_f32_32x32x16_f16 v[2:17], v[186:189], v[194:197], v[2:17]
	v_add_u32_e32 v230, s23, v230
	v_add_u32_e32 v234, s23, v234
	s_waitcnt lgkmcnt(5)
	v_mfma_f32_32x32x16_f16 v[18:33], v[186:189], v[198:201], v[18:33]
	v_add_u32_e32 v231, s23, v231
	v_add_u32_e32 v235, s23, v235
	s_waitcnt lgkmcnt(4)
	v_mfma_f32_32x32x16_f16 v[34:49], v[190:193], v[194:197], v[34:49]
	v_add_u32_e32 v232, s23, v232
	v_add_u32_e32 v237, s23, v237
	v_mfma_f32_32x32x16_f16 v[50:65], v[190:193], v[198:201], v[50:65]
	v_add_u32_e32 v233, s23, v233
	v_add_u32_e32 v180, s23, v180
	s_waitcnt lgkmcnt(0)
	s_waitcnt vmcnt(6)
	s_barrier
	ds_read_b128 v[186:189], v234
	ds_read_b128 v[194:197], v230
	ds_read_b128 v[198:201], v230 offset:4096
	ds_read_b128 v[190:193], v234 offset:4096
	s_add_i32 s28, s20, s22
	s_add_i32 s29, s20, s25
	s_add_i32 m0, s28, 0x0
	v_mfma_f32_32x32x16_f16 v[2:17], v[162:165], v[170:173], v[2:17]
	global_load_lds_dwordx4 v181, s[16:17]
	s_add_i32 m0, s28, 0x400
	v_mfma_f32_32x32x16_f16 v[18:33], v[162:165], v[174:177], v[18:33]
	global_load_lds_dwordx4 v182, s[16:17]
	s_add_i32 m0, s28, 0x800
	v_mfma_f32_32x32x16_f16 v[34:49], v[166:169], v[170:173], v[34:49]
	global_load_lds_dwordx4 v183, s[16:17]
	s_add_i32 m0, s28, 0xc00
	v_mfma_f32_32x32x16_f16 v[50:65], v[166:169], v[174:177], v[50:65]
	global_load_lds_dwordx4 v224, s[16:17]
	ds_read_b128 v[162:165], v235
	ds_read_b128 v[170:173], v231
	ds_read_b128 v[174:177], v231 offset:4096
	ds_read_b128 v[166:169], v235 offset:4096
	s_waitcnt lgkmcnt(6)
	s_add_i32 m0, s29, 0x0
	v_mfma_f32_32x32x16_f16 v[2:17], v[186:189], v[194:197], v[2:17]
	global_load_lds_dwordx4 v227, s[18:19]
	s_waitcnt lgkmcnt(5)
	s_add_i32 m0, s29, 0x400
	v_mfma_f32_32x32x16_f16 v[18:33], v[186:189], v[198:201], v[18:33]
	global_load_lds_dwordx4 v229, s[18:19]
	s_waitcnt lgkmcnt(4)
	v_mfma_f32_32x32x16_f16 v[34:49], v[190:193], v[194:197], v[34:49]
	s_add_u32 s16, s16, 0x80
	s_addc_u32 s17, s17, 0
	v_mfma_f32_32x32x16_f16 v[50:65], v[190:193], v[198:201], v[50:65]
	s_add_u32 s18, s18, 0x80
	s_addc_u32 s19, s19, 0
	ds_read_b128 v[186:189], v237
	ds_read_b128 v[194:197], v232
	ds_read_b128 v[198:201], v232 offset:4096
	ds_read_b128 v[190:193], v237 offset:4096
	s_add_i32 s20, s20, 0xc000
	s_cmp_eq_u32 s20, 0x24000
	s_cselect_b32 s20, 0, s20
	s_waitcnt lgkmcnt(6)
	v_mfma_f32_32x32x16_f16 v[2:17], v[162:165], v[170:173], v[2:17]
	s_add_i32 s30, s21, 0xc000
	s_waitcnt lgkmcnt(5)
	v_mfma_f32_32x32x16_f16 v[18:33], v[162:165], v[174:177], v[18:33]
	s_cmp_eq_u32 s30, 0x24000
	s_waitcnt lgkmcnt(4)
	v_mfma_f32_32x32x16_f16 v[34:49], v[166:169], v[170:173], v[34:49]
	s_cselect_b32 s30, 0, s30
	v_mfma_f32_32x32x16_f16 v[50:65], v[166:169], v[174:177], v[50:65]
	s_sub_i32 s23, s30, s21
	s_mov_b32 s21, s30
	ds_read_b128 v[162:165], v180
	ds_read_b128 v[170:173], v233
	ds_read_b128 v[174:177], v233 offset:4096
	ds_read_b128 v[166:169], v180 offset:4096
	s_waitcnt lgkmcnt(6)
	v_mfma_f32_32x32x16_f16 v[2:17], v[186:189], v[194:197], v[2:17]
	v_add_u32_e32 v230, s23, v230
	v_add_u32_e32 v234, s23, v234
	s_waitcnt lgkmcnt(5)
	v_mfma_f32_32x32x16_f16 v[18:33], v[186:189], v[198:201], v[18:33]
	v_add_u32_e32 v231, s23, v231
	v_add_u32_e32 v235, s23, v235
	s_waitcnt lgkmcnt(4)
	v_mfma_f32_32x32x16_f16 v[34:49], v[190:193], v[194:197], v[34:49]
	v_add_u32_e32 v232, s23, v232
	v_add_u32_e32 v237, s23, v237
	v_mfma_f32_32x32x16_f16 v[50:65], v[190:193], v[198:201], v[50:65]
	v_add_u32_e32 v233, s23, v233
	v_add_u32_e32 v180, s23, v180
	s_waitcnt lgkmcnt(0)
	v_mfma_f32_32x32x16_f16 v[2:17], v[162:165], v[170:173], v[2:17]
	v_mfma_f32_32x32x16_f16 v[18:33], v[162:165], v[174:177], v[18:33]
	v_mfma_f32_32x32x16_f16 v[34:49], v[166:169], v[170:173], v[34:49]
	v_mfma_f32_32x32x16_f16 v[50:65], v[166:169], v[174:177], v[50:65]
	s_nop 15
	s_waitcnt vmcnt(6)
	s_barrier
	ds_read_b128 v[186:189], v234
	ds_read_b128 v[194:197], v230
	ds_read_b128 v[198:201], v230 offset:4096
	ds_read_b128 v[190:193], v234 offset:4096
	s_add_i32 s28, s20, s22
	s_add_i32 s29, s20, s25
	s_add_i32 m0, s28, 0x0
	s_nop 0
	global_load_lds_dwordx4 v181, s[16:17]
	s_add_i32 m0, s28, 0x400
	s_nop 0
	global_load_lds_dwordx4 v182, s[16:17]
	s_add_i32 m0, s28, 0x800
	s_nop 0
	global_load_lds_dwordx4 v183, s[16:17]
	s_add_i32 m0, s28, 0xc00
	s_nop 0
	global_load_lds_dwordx4 v224, s[16:17]
	ds_read_b128 v[162:165], v235
	ds_read_b128 v[170:173], v231
	ds_read_b128 v[174:177], v231 offset:4096
	ds_read_b128 v[166:169], v235 offset:4096
	s_waitcnt lgkmcnt(6)
	s_add_i32 m0, s29, 0x0
	v_mfma_f32_32x32x16_bf16 v[130:145], v[186:189], v[194:197], 0
	v_mul_f32_e32 v2, v218, v2
	v_mul_f32_e32 v3, v218, v3
	v_mul_f32_e32 v4, v218, v4
	v_mul_f32_e32 v5, v218, v5
	v_mul_f32_e32 v6, v218, v6
	v_mul_f32_e32 v7, v218, v7
	global_load_lds_dwordx4 v227, s[18:19]
	s_waitcnt lgkmcnt(5)
	s_add_i32 m0, s29, 0x400
	v_mfma_f32_32x32x16_bf16 v[146:161], v[186:189], v[198:201], 0
	v_mul_f32_e32 v8, v218, v8
	v_mul_f32_e32 v9, v218, v9
	v_mul_f32_e32 v2, 0xbfb8aa3b, v2
	v_mul_f32_e32 v3, 0xbfb8aa3b, v3
	v_mul_f32_e32 v4, 0xbfb8aa3b, v4
	v_mul_f32_e32 v5, 0xbfb8aa3b, v5
	global_load_lds_dwordx4 v229, s[18:19]
	s_waitcnt lgkmcnt(4)
	v_mfma_f32_32x32x16_bf16 v[238:253], v[190:193], v[194:197], 0
	v_mul_f32_e32 v6, 0xbfb8aa3b, v6
	v_mul_f32_e32 v7, 0xbfb8aa3b, v7
	v_mul_f32_e32 v8, 0xbfb8aa3b, v8
	v_mul_f32_e32 v9, 0xbfb8aa3b, v9
	v_exp_f32_e32 v2, v2
	v_exp_f32_e32 v3, v3
	s_add_u32 s16, s16, 0x80
	s_addc_u32 s17, s17, 0
	v_mfma_f32_32x32x16_bf16 v[202:217], v[190:193], v[198:201], 0
	v_exp_f32_e32 v4, v4
	v_exp_f32_e32 v5, v5
	v_exp_f32_e32 v6, v6
	v_exp_f32_e32 v7, v7
	v_exp_f32_e32 v8, v8
	v_exp_f32_e32 v9, v9
	s_add_u32 s18, s18, 0x80
	s_addc_u32 s19, s19, 0
	ds_read_b128 v[186:189], v237
	ds_read_b128 v[194:197], v232
	ds_read_b128 v[198:201], v232 offset:4096
	ds_read_b128 v[190:193], v237 offset:4096
	s_add_i32 s20, s20, 0xc000
	s_cmp_eq_u32 s20, 0x24000
	s_cselect_b32 s20, 0, s20
	s_waitcnt lgkmcnt(6)
	v_mfma_f32_32x32x16_bf16 v[130:145], v[162:165], v[170:173], v[130:145]
	v_add_f32_e32 v2, 1.0, v2
	v_add_f32_e32 v3, 1.0, v3
	v_add_f32_e32 v4, 1.0, v4
	v_add_f32_e32 v5, 1.0, v5
	v_add_f32_e32 v6, 1.0, v6
	v_add_f32_e32 v7, 1.0, v7
	s_add_i32 s30, s21, 0xc000
	s_waitcnt lgkmcnt(5)
	v_mfma_f32_32x32x16_bf16 v[146:161], v[162:165], v[174:177], v[146:161]
	v_add_f32_e32 v8, 1.0, v8
	v_add_f32_e32 v9, 1.0, v9
	v_rcp_f32_e32 v2, v2
	v_rcp_f32_e32 v3, v3
	v_rcp_f32_e32 v4, v4
	v_rcp_f32_e32 v5, v5
	s_cmp_eq_u32 s30, 0x24000
	s_waitcnt lgkmcnt(4)
	v_mfma_f32_32x32x16_bf16 v[238:253], v[166:169], v[170:173], v[238:253]
	v_rcp_f32_e32 v6, v6
	v_rcp_f32_e32 v7, v7
	v_rcp_f32_e32 v8, v8
	v_rcp_f32_e32 v9, v9
	v_cvt_pk_bf16_f32 v2, v2, v3
	v_cvt_pk_bf16_f32 v3, v4, v5
	s_cselect_b32 s30, 0, s30
	v_mfma_f32_32x32x16_bf16 v[202:217], v[166:169], v[174:177], v[202:217]
	v_cvt_pk_bf16_f32 v4, v6, v7
	v_cvt_pk_bf16_f32 v5, v8, v9
	v_mul_f32_e32 v10, v218, v10
	v_mul_f32_e32 v11, v218, v11
	v_mul_f32_e32 v12, v218, v12
	v_mul_f32_e32 v13, v218, v13
	s_sub_i32 s23, s30, s21
	s_mov_b32 s21, s30
	ds_read_b128 v[162:165], v180
	ds_read_b128 v[170:173], v233
	ds_read_b128 v[174:177], v233 offset:4096
	ds_read_b128 v[166:169], v180 offset:4096
	s_waitcnt lgkmcnt(6)
	v_mfma_f32_32x32x16_bf16 v[130:145], v[186:189], v[194:197], v[130:145]
	v_mul_f32_e32 v14, v218, v14
	v_mul_f32_e32 v15, v218, v15
	v_mul_f32_e32 v16, v218, v16
	v_mul_f32_e32 v17, v218, v17
	v_mul_f32_e32 v10, 0xbfb8aa3b, v10
	v_mul_f32_e32 v11, 0xbfb8aa3b, v11
	v_add_u32_e32 v230, s23, v230
	v_add_u32_e32 v234, s23, v234
	s_waitcnt lgkmcnt(5)
	v_mfma_f32_32x32x16_bf16 v[146:161], v[186:189], v[198:201], v[146:161]
	v_mul_f32_e32 v12, 0xbfb8aa3b, v12
	v_mul_f32_e32 v13, 0xbfb8aa3b, v13
	v_mul_f32_e32 v14, 0xbfb8aa3b, v14
	v_mul_f32_e32 v15, 0xbfb8aa3b, v15
	v_mul_f32_e32 v16, 0xbfb8aa3b, v16
	v_mul_f32_e32 v17, 0xbfb8aa3b, v17
	v_add_u32_e32 v231, s23, v231
	v_add_u32_e32 v235, s23, v235
	s_waitcnt lgkmcnt(4)
	v_mfma_f32_32x32x16_bf16 v[238:253], v[190:193], v[194:197], v[238:253]
	v_exp_f32_e32 v10, v10
	v_exp_f32_e32 v11, v11
	v_exp_f32_e32 v12, v12
	v_exp_f32_e32 v13, v13
	v_exp_f32_e32 v14, v14
	v_exp_f32_e32 v15, v15
	v_add_u32_e32 v232, s23, v232
	v_add_u32_e32 v237, s23, v237
	v_mfma_f32_32x32x16_bf16 v[202:217], v[190:193], v[198:201], v[202:217]
	v_exp_f32_e32 v16, v16
	v_exp_f32_e32 v17, v17
	v_add_f32_e32 v10, 1.0, v10
	v_add_f32_e32 v11, 1.0, v11
	v_add_f32_e32 v12, 1.0, v12
	v_add_f32_e32 v13, 1.0, v13
	v_add_u32_e32 v233, s23, v233
	v_add_u32_e32 v180, s23, v180
	s_waitcnt lgkmcnt(0)
	s_waitcnt vmcnt(6)
	s_barrier
	ds_read_b128 v[186:189], v234
	ds_read_b128 v[194:197], v230
	ds_read_b128 v[198:201], v230 offset:4096
	ds_read_b128 v[190:193], v234 offset:4096
	s_add_i32 s28, s20, s22
	s_add_i32 s29, s20, s25
	s_add_i32 m0, s28, 0x0
	v_mfma_f32_32x32x16_bf16 v[130:145], v[162:165], v[170:173], v[130:145]
	v_add_f32_e32 v14, 1.0, v14
	v_add_f32_e32 v15, 1.0, v15
	v_add_f32_e32 v16, 1.0, v16
	v_add_f32_e32 v17, 1.0, v17
	v_rcp_f32_e32 v10, v10
	v_rcp_f32_e32 v11, v11
	global_load_lds_dwordx4 v181, s[16:17]
	s_add_i32 m0, s28, 0x400
	v_mfma_f32_32x32x16_bf16 v[146:161], v[162:165], v[174:177], v[146:161]
	v_rcp_f32_e32 v12, v12
	v_rcp_f32_e32 v13, v13
	v_rcp_f32_e32 v14, v14
	v_rcp_f32_e32 v15, v15
	v_rcp_f32_e32 v16, v16
	v_rcp_f32_e32 v17, v17
	global_load_lds_dwordx4 v182, s[16:17]
	s_add_i32 m0, s28, 0x800
	v_mfma_f32_32x32x16_bf16 v[238:253], v[166:169], v[170:173], v[238:253]
	v_cvt_pk_bf16_f32 v6, v10, v11
	v_cvt_pk_bf16_f32 v7, v12, v13
	v_cvt_pk_bf16_f32 v8, v14, v15
	v_cvt_pk_bf16_f32 v9, v16, v17
	v_mul_f32_e32 v18, v219, v18
	v_mul_f32_e32 v19, v219, v19
	global_load_lds_dwordx4 v183, s[16:17]
	s_add_i32 m0, s28, 0xc00
	v_mfma_f32_32x32x16_bf16 v[202:217], v[166:169], v[174:177], v[202:217]
	v_mul_f32_e32 v20, v219, v20
	v_mul_f32_e32 v21, v219, v21
	v_mul_f32_e32 v22, v219, v22
	v_mul_f32_e32 v23, v219, v23
	v_mul_f32_e32 v24, v219, v24
	v_mul_f32_e32 v25, v219, v25
	global_load_lds_dwordx4 v224, s[16:17]
	ds_read_b128 v[162:165], v235
	ds_read_b128 v[170:173], v231
	ds_read_b128 v[174:177], v231 offset:4096
	ds_read_b128 v[166:169], v235 offset:4096
	s_waitcnt lgkmcnt(6)
	s_add_i32 m0, s29, 0x0
	v_mfma_f32_32x32x16_bf16 v[130:145], v[186:189], v[194:197], v[130:145]
	v_mul_f32_e32 v18, 0xbfb8aa3b, v18
	v_mul_f32_e32 v19, 0xbfb8aa3b, v19
	v_mul_f32_e32 v20, 0xbfb8aa3b, v20
	v_mul_f32_e32 v21, 0xbfb8aa3b, v21
	v_mul_f32_e32 v22, 0xbfb8aa3b, v22
	v_mul_f32_e32 v23, 0xbfb8aa3b, v23
	global_load_lds_dwordx4 v227, s[18:19]
	s_waitcnt lgkmcnt(5)
	s_add_i32 m0, s29, 0x400
	v_mfma_f32_32x32x16_bf16 v[146:161], v[186:189], v[198:201], v[146:161]
	v_mul_f32_e32 v24, 0xbfb8aa3b, v24
	v_mul_f32_e32 v25, 0xbfb8aa3b, v25
	v_exp_f32_e32 v18, v18
	v_exp_f32_e32 v19, v19
	v_exp_f32_e32 v20, v20
	v_exp_f32_e32 v21, v21
	global_load_lds_dwordx4 v229, s[18:19]
	s_waitcnt lgkmcnt(4)
	v_mfma_f32_32x32x16_bf16 v[238:253], v[190:193], v[194:197], v[238:253]
	v_exp_f32_e32 v22, v22
	v_exp_f32_e32 v23, v23
	v_exp_f32_e32 v24, v24
	v_exp_f32_e32 v25, v25
	v_add_f32_e32 v18, 1.0, v18
	v_add_f32_e32 v19, 1.0, v19
	s_add_u32 s16, s16, 0x80
	s_addc_u32 s17, s17, 0
	v_mfma_f32_32x32x16_bf16 v[202:217], v[190:193], v[198:201], v[202:217]
	v_add_f32_e32 v20, 1.0, v20
	v_add_f32_e32 v21, 1.0, v21
	v_add_f32_e32 v22, 1.0, v22
	v_add_f32_e32 v23, 1.0, v23
	v_add_f32_e32 v24, 1.0, v24
	v_add_f32_e32 v25, 1.0, v25
	s_add_u32 s18, s18, 0x80
	s_addc_u32 s19, s19, 0
	ds_read_b128 v[186:189], v237
	ds_read_b128 v[194:197], v232
	ds_read_b128 v[198:201], v232 offset:4096
	ds_read_b128 v[190:193], v237 offset:4096
	s_add_i32 s20, s20, 0xc000
	s_cmp_eq_u32 s20, 0x24000
	s_cselect_b32 s20, 0, s20
	s_waitcnt lgkmcnt(6)
	v_mfma_f32_32x32x16_bf16 v[130:145], v[162:165], v[170:173], v[130:145]
	v_rcp_f32_e32 v18, v18
	v_rcp_f32_e32 v19, v19
	v_rcp_f32_e32 v20, v20
	v_rcp_f32_e32 v21, v21
	v_rcp_f32_e32 v22, v22
	v_rcp_f32_e32 v23, v23
	s_add_i32 s30, s21, 0xc000
	s_waitcnt lgkmcnt(5)
	v_mfma_f32_32x32x16_bf16 v[146:161], v[162:165], v[174:177], v[146:161]
	v_rcp_f32_e32 v24, v24
	v_rcp_f32_e32 v25, v25
	v_cvt_pk_bf16_f32 v18, v18, v19
	v_cvt_pk_bf16_f32 v19, v20, v21
	v_cvt_pk_bf16_f32 v20, v22, v23
	v_cvt_pk_bf16_f32 v21, v24, v25
	s_cmp_eq_u32 s30, 0x24000
	s_waitcnt lgkmcnt(4)
	v_mfma_f32_32x32x16_bf16 v[238:253], v[166:169], v[170:173], v[238:253]
	v_mul_f32_e32 v26, v219, v26
	v_mul_f32_e32 v27, v219, v27
	v_mul_f32_e32 v28, v219, v28
	v_mul_f32_e32 v29, v219, v29
	v_mul_f32_e32 v30, v219, v30
	v_mul_f32_e32 v31, v219, v31
	s_cselect_b32 s30, 0, s30
	v_mfma_f32_32x32x16_bf16 v[202:217], v[166:169], v[174:177], v[202:217]
	v_mul_f32_e32 v32, v219, v32
	v_mul_f32_e32 v33, v219, v33
	v_mul_f32_e32 v26, 0xbfb8aa3b, v26
	v_mul_f32_e32 v27, 0xbfb8aa3b, v27
	v_mul_f32_e32 v28, 0xbfb8aa3b, v28
	v_mul_f32_e32 v29, 0xbfb8aa3b, v29
	s_sub_i32 s23, s30, s21
	s_mov_b32 s21, s30
	ds_read_b128 v[162:165], v180
	ds_read_b128 v[170:173], v233
	ds_read_b128 v[174:177], v233 offset:4096
	ds_read_b128 v[166:169], v180 offset:4096
	s_waitcnt lgkmcnt(6)
	v_mfma_f32_32x32x16_bf16 v[130:145], v[186:189], v[194:197], v[130:145]
	v_mul_f32_e32 v30, 0xbfb8aa3b, v30
	v_mul_f32_e32 v31, 0xbfb8aa3b, v31
	v_mul_f32_e32 v32, 0xbfb8aa3b, v32
	v_mul_f32_e32 v33, 0xbfb8aa3b, v33
	v_exp_f32_e32 v26, v26
	v_exp_f32_e32 v27, v27
	v_add_u32_e32 v230, s23, v230
	v_add_u32_e32 v234, s23, v234
	s_waitcnt lgkmcnt(5)
	v_mfma_f32_32x32x16_bf16 v[146:161], v[186:189], v[198:201], v[146:161]
	v_exp_f32_e32 v28, v28
	v_exp_f32_e32 v29, v29
	v_exp_f32_e32 v30, v30
	v_exp_f32_e32 v31, v31
	v_exp_f32_e32 v32, v32
	v_exp_f32_e32 v33, v33
	v_add_u32_e32 v231, s23, v231
	v_add_u32_e32 v235, s23, v235
	s_waitcnt lgkmcnt(4)
	v_mfma_f32_32x32x16_bf16 v[238:253], v[190:193], v[194:197], v[238:253]
	v_add_f32_e32 v26, 1.0, v26
	v_add_f32_e32 v27, 1.0, v27
	v_add_f32_e32 v28, 1.0, v28
	v_add_f32_e32 v29, 1.0, v29
	v_add_f32_e32 v30, 1.0, v30
	v_add_f32_e32 v31, 1.0, v31
	v_add_u32_e32 v232, s23, v232
	v_add_u32_e32 v237, s23, v237
	v_mfma_f32_32x32x16_bf16 v[202:217], v[190:193], v[198:201], v[202:217]
	v_add_f32_e32 v32, 1.0, v32
	v_add_f32_e32 v33, 1.0, v33
	v_rcp_f32_e32 v26, v26
	v_rcp_f32_e32 v27, v27
	v_rcp_f32_e32 v28, v28
	v_rcp_f32_e32 v29, v29
	v_add_u32_e32 v233, s23, v233
	v_add_u32_e32 v180, s23, v180
	s_waitcnt lgkmcnt(0)
	s_waitcnt vmcnt(6)
	s_barrier
	ds_read_b128 v[186:189], v234
	ds_read_b128 v[194:197], v230
	ds_read_b128 v[198:201], v230 offset:4096
	ds_read_b128 v[190:193], v234 offset:4096
	s_add_i32 s28, s20, s22
	s_add_i32 s29, s20, s25
	s_add_i32 m0, s28, 0x0
	v_mfma_f32_32x32x16_bf16 v[130:145], v[162:165], v[170:173], v[130:145]
	v_rcp_f32_e32 v30, v30
	v_rcp_f32_e32 v31, v31
	v_rcp_f32_e32 v32, v32
	v_rcp_f32_e32 v33, v33
	v_cvt_pk_bf16_f32 v22, v26, v27
	v_cvt_pk_bf16_f32 v23, v28, v29
	global_load_lds_dwordx4 v181, s[34:35]
	s_add_i32 m0, s28, 0x400
	v_mfma_f32_32x32x16_bf16 v[146:161], v[162:165], v[174:177], v[146:161]
	v_cvt_pk_bf16_f32 v24, v30, v31
	v_cvt_pk_bf16_f32 v25, v32, v33
	v_mul_f32_e32 v34, v218, v34
	v_mul_f32_e32 v35, v218, v35
	v_mul_f32_e32 v36, v218, v36
	v_mul_f32_e32 v37, v218, v37
	global_load_lds_dwordx4 v182, s[34:35]
	s_add_i32 m0, s28, 0x800
	v_mfma_f32_32x32x16_bf16 v[238:253], v[166:169], v[170:173], v[238:253]
	v_mul_f32_e32 v38, v218, v38
	v_mul_f32_e32 v39, v218, v39
	v_mul_f32_e32 v40, v218, v40
	v_mul_f32_e32 v41, v218, v41
	v_mul_f32_e32 v34, 0xbfb8aa3b, v34
	v_mul_f32_e32 v35, 0xbfb8aa3b, v35
	global_load_lds_dwordx4 v183, s[34:35]
	s_add_i32 m0, s28, 0xc00
	v_mfma_f32_32x32x16_bf16 v[202:217], v[166:169], v[174:177], v[202:217]
	v_mul_f32_e32 v36, 0xbfb8aa3b, v36
	v_mul_f32_e32 v37, 0xbfb8aa3b, v37
	v_mul_f32_e32 v38, 0xbfb8aa3b, v38
	v_mul_f32_e32 v39, 0xbfb8aa3b, v39
	v_mul_f32_e32 v40, 0xbfb8aa3b, v40
	v_mul_f32_e32 v41, 0xbfb8aa3b, v41
	global_load_lds_dwordx4 v224, s[34:35]
	ds_read_b128 v[162:165], v235
	ds_read_b128 v[170:173], v231
	ds_read_b128 v[174:177], v231 offset:4096
	ds_read_b128 v[166:169], v235 offset:4096
	s_waitcnt lgkmcnt(6)
	s_add_i32 m0, s29, 0x0
	v_mfma_f32_32x32x16_bf16 v[130:145], v[186:189], v[194:197], v[130:145]
	v_exp_f32_e32 v34, v34
	v_exp_f32_e32 v35, v35
	v_exp_f32_e32 v36, v36
	v_exp_f32_e32 v37, v37
	v_exp_f32_e32 v38, v38
	v_exp_f32_e32 v39, v39
	global_load_lds_dwordx4 v225, s[36:37]
	s_waitcnt lgkmcnt(5)
	s_add_i32 m0, s29, 0x400
	v_mfma_f32_32x32x16_bf16 v[146:161], v[186:189], v[198:201], v[146:161]
	v_exp_f32_e32 v40, v40
	v_exp_f32_e32 v41, v41
	v_add_f32_e32 v34, 1.0, v34
	v_add_f32_e32 v35, 1.0, v35
	v_add_f32_e32 v36, 1.0, v36
	v_add_f32_e32 v37, 1.0, v37
	global_load_lds_dwordx4 v226, s[36:37]
	s_waitcnt lgkmcnt(4)
	v_mfma_f32_32x32x16_bf16 v[238:253], v[190:193], v[194:197], v[238:253]
	v_add_f32_e32 v38, 1.0, v38
	v_add_f32_e32 v39, 1.0, v39
	v_add_f32_e32 v40, 1.0, v40
	v_add_f32_e32 v41, 1.0, v41
	v_rcp_f32_e32 v34, v34
	v_rcp_f32_e32 v35, v35
	s_add_u32 s34, s34, 0x80
	s_addc_u32 s35, s35, 0
	v_mfma_f32_32x32x16_bf16 v[202:217], v[190:193], v[198:201], v[202:217]
	v_rcp_f32_e32 v36, v36
	v_rcp_f32_e32 v37, v37
	v_rcp_f32_e32 v38, v38
	v_rcp_f32_e32 v39, v39
	v_rcp_f32_e32 v40, v40
	v_rcp_f32_e32 v41, v41
	s_add_u32 s36, s36, 0x80
	s_addc_u32 s37, s37, 0
	ds_read_b128 v[186:189], v237
	ds_read_b128 v[194:197], v232
	ds_read_b128 v[198:201], v232 offset:4096
	ds_read_b128 v[190:193], v237 offset:4096
	s_add_i32 s20, s20, 0xc000
	s_cmp_eq_u32 s20, 0x24000
	s_cselect_b32 s20, 0, s20
	s_waitcnt lgkmcnt(6)
	v_mfma_f32_32x32x16_bf16 v[130:145], v[162:165], v[170:173], v[130:145]
	v_cvt_pk_bf16_f32 v34, v34, v35
	v_cvt_pk_bf16_f32 v35, v36, v37
	v_cvt_pk_bf16_f32 v36, v38, v39
	v_cvt_pk_bf16_f32 v37, v40, v41
	v_mul_f32_e32 v42, v218, v42
	v_mul_f32_e32 v43, v218, v43
	s_add_i32 s30, s21, 0xc000
	s_waitcnt lgkmcnt(5)
	v_mfma_f32_32x32x16_bf16 v[146:161], v[162:165], v[174:177], v[146:161]
	v_mul_f32_e32 v44, v218, v44
	v_mul_f32_e32 v45, v218, v45
	v_mul_f32_e32 v46, v218, v46
	v_mul_f32_e32 v47, v218, v47
	v_mul_f32_e32 v48, v218, v48
	v_mul_f32_e32 v49, v218, v49
	s_cmp_eq_u32 s30, 0x24000
	s_waitcnt lgkmcnt(4)
	v_mfma_f32_32x32x16_bf16 v[238:253], v[166:169], v[170:173], v[238:253]
	v_mul_f32_e32 v42, 0xbfb8aa3b, v42
	v_mul_f32_e32 v43, 0xbfb8aa3b, v43
	v_mul_f32_e32 v44, 0xbfb8aa3b, v44
	v_mul_f32_e32 v45, 0xbfb8aa3b, v45
	v_mul_f32_e32 v46, 0xbfb8aa3b, v46
	v_mul_f32_e32 v47, 0xbfb8aa3b, v47
	s_cselect_b32 s30, 0, s30
	v_mfma_f32_32x32x16_bf16 v[202:217], v[166:169], v[174:177], v[202:217]
	v_mul_f32_e32 v48, 0xbfb8aa3b, v48
	v_mul_f32_e32 v49, 0xbfb8aa3b, v49
	v_exp_f32_e32 v42, v42
	v_exp_f32_e32 v43, v43
	v_exp_f32_e32 v44, v44
	v_exp_f32_e32 v45, v45
	s_sub_i32 s23, s30, s21
	s_mov_b32 s21, s30
	ds_read_b128 v[162:165], v180
	ds_read_b128 v[170:173], v233
	ds_read_b128 v[174:177], v233 offset:4096
	ds_read_b128 v[166:169], v180 offset:4096
	s_waitcnt lgkmcnt(6)
	v_mfma_f32_32x32x16_bf16 v[130:145], v[186:189], v[194:197], v[130:145]
	v_exp_f32_e32 v46, v46
	v_exp_f32_e32 v47, v47
	v_exp_f32_e32 v48, v48
	v_exp_f32_e32 v49, v49
	v_add_f32_e32 v42, 1.0, v42
	v_add_f32_e32 v43, 1.0, v43
	v_add_u32_e32 v230, s23, v230
	v_add_u32_e32 v234, s23, v234
	s_waitcnt lgkmcnt(5)
	v_mfma_f32_32x32x16_bf16 v[146:161], v[186:189], v[198:201], v[146:161]
	v_add_f32_e32 v44, 1.0, v44
	v_add_f32_e32 v45, 1.0, v45
	v_add_f32_e32 v46, 1.0, v46
	v_add_f32_e32 v47, 1.0, v47
	v_add_f32_e32 v48, 1.0, v48
	v_add_f32_e32 v49, 1.0, v49
	v_add_u32_e32 v231, s23, v231
	v_add_u32_e32 v235, s23, v235
	s_waitcnt lgkmcnt(4)
	v_mfma_f32_32x32x16_bf16 v[238:253], v[190:193], v[194:197], v[238:253]
	v_rcp_f32_e32 v42, v42
	v_rcp_f32_e32 v43, v43
	v_rcp_f32_e32 v44, v44
	v_rcp_f32_e32 v45, v45
	v_rcp_f32_e32 v46, v46
	v_rcp_f32_e32 v47, v47
	v_add_u32_e32 v232, s23, v232
	v_add_u32_e32 v237, s23, v237
	v_mfma_f32_32x32x16_bf16 v[202:217], v[190:193], v[198:201], v[202:217]
	v_rcp_f32_e32 v48, v48
	v_rcp_f32_e32 v49, v49
	v_cvt_pk_bf16_f32 v38, v42, v43
	v_cvt_pk_bf16_f32 v39, v44, v45
	v_cvt_pk_bf16_f32 v40, v46, v47
	v_cvt_pk_bf16_f32 v41, v48, v49
	v_add_u32_e32 v233, s23, v233
	v_add_u32_e32 v180, s23, v180
	s_waitcnt lgkmcnt(0)
	s_waitcnt vmcnt(6)
	s_barrier
	ds_read_b128 v[186:189], v234
	ds_read_b128 v[194:197], v230
	ds_read_b128 v[198:201], v230 offset:4096
	ds_read_b128 v[190:193], v234 offset:4096
	s_add_i32 s28, s20, s22
	s_add_i32 s29, s20, s25
	s_add_i32 m0, s28, 0x0
	v_mfma_f32_32x32x16_bf16 v[130:145], v[162:165], v[170:173], v[130:145]
	v_mul_f32_e32 v50, v219, v50
	v_mul_f32_e32 v51, v219, v51
	v_mul_f32_e32 v52, v219, v52
	v_mul_f32_e32 v53, v219, v53
	v_mul_f32_e32 v54, v219, v54
	v_mul_f32_e32 v55, v219, v55
	global_load_lds_dwordx4 v181, s[34:35]
	s_add_i32 m0, s28, 0x400
	v_mfma_f32_32x32x16_bf16 v[146:161], v[162:165], v[174:177], v[146:161]
	v_mul_f32_e32 v56, v219, v56
	v_mul_f32_e32 v57, v219, v57
	v_mul_f32_e32 v50, 0xbfb8aa3b, v50
	v_mul_f32_e32 v51, 0xbfb8aa3b, v51
	v_mul_f32_e32 v52, 0xbfb8aa3b, v52
	v_mul_f32_e32 v53, 0xbfb8aa3b, v53
	global_load_lds_dwordx4 v182, s[34:35]
	s_add_i32 m0, s28, 0x800
	v_mfma_f32_32x32x16_bf16 v[238:253], v[166:169], v[170:173], v[238:253]
	v_mul_f32_e32 v54, 0xbfb8aa3b, v54
	v_mul_f32_e32 v55, 0xbfb8aa3b, v55
	v_mul_f32_e32 v56, 0xbfb8aa3b, v56
	v_mul_f32_e32 v57, 0xbfb8aa3b, v57
	v_exp_f32_e32 v50, v50
	v_exp_f32_e32 v51, v51
	global_load_lds_dwordx4 v183, s[34:35]
	s_add_i32 m0, s28, 0xc00
	v_mfma_f32_32x32x16_bf16 v[202:217], v[166:169], v[174:177], v[202:217]
	v_exp_f32_e32 v52, v52
	v_exp_f32_e32 v53, v53
	v_exp_f32_e32 v54, v54
	v_exp_f32_e32 v55, v55
	v_exp_f32_e32 v56, v56
	v_exp_f32_e32 v57, v57
	global_load_lds_dwordx4 v224, s[34:35]
	ds_read_b128 v[162:165], v235
	ds_read_b128 v[170:173], v231
	ds_read_b128 v[174:177], v231 offset:4096
	ds_read_b128 v[166:169], v235 offset:4096
	s_waitcnt lgkmcnt(6)
	s_add_i32 m0, s29, 0x0
	v_mfma_f32_32x32x16_bf16 v[130:145], v[186:189], v[194:197], v[130:145]
	v_add_f32_e32 v50, 1.0, v50
	v_add_f32_e32 v51, 1.0, v51
	v_add_f32_e32 v52, 1.0, v52
	v_add_f32_e32 v53, 1.0, v53
	v_add_f32_e32 v54, 1.0, v54
	v_add_f32_e32 v55, 1.0, v55
	global_load_lds_dwordx4 v225, s[36:37]
	s_waitcnt lgkmcnt(5)
	s_add_i32 m0, s29, 0x400
	v_mfma_f32_32x32x16_bf16 v[146:161], v[186:189], v[198:201], v[146:161]
	v_add_f32_e32 v56, 1.0, v56
	v_add_f32_e32 v57, 1.0, v57
	v_rcp_f32_e32 v50, v50
	v_rcp_f32_e32 v51, v51
	v_rcp_f32_e32 v52, v52
	v_rcp_f32_e32 v53, v53
	global_load_lds_dwordx4 v226, s[36:37]
	s_waitcnt lgkmcnt(4)
	v_mfma_f32_32x32x16_bf16 v[238:253], v[190:193], v[194:197], v[238:253]
	v_rcp_f32_e32 v54, v54
	v_rcp_f32_e32 v55, v55
	v_rcp_f32_e32 v56, v56
	v_rcp_f32_e32 v57, v57
	v_cvt_pk_bf16_f32 v50, v50, v51
	v_cvt_pk_bf16_f32 v51, v52, v53
	s_add_u32 s34, s34, 0x80
	s_addc_u32 s35, s35, 0
	v_mfma_f32_32x32x16_bf16 v[202:217], v[190:193], v[198:201], v[202:217]
	v_cvt_pk_bf16_f32 v52, v54, v55
	v_cvt_pk_bf16_f32 v53, v56, v57
	v_mul_f32_e32 v58, v219, v58
	v_mul_f32_e32 v59, v219, v59
	v_mul_f32_e32 v60, v219, v60
	v_mul_f32_e32 v61, v219, v61
	s_add_u32 s36, s36, 0x80
	s_addc_u32 s37, s37, 0
	ds_read_b128 v[186:189], v237
	ds_read_b128 v[194:197], v232
	ds_read_b128 v[198:201], v232 offset:4096
	ds_read_b128 v[190:193], v237 offset:4096
	s_add_i32 s20, s20, 0xc000
	s_cmp_eq_u32 s20, 0x24000
	s_cselect_b32 s20, 0, s20
	s_waitcnt lgkmcnt(6)
	v_mfma_f32_32x32x16_bf16 v[130:145], v[162:165], v[170:173], v[130:145]
	v_mul_f32_e32 v62, v219, v62
	v_mul_f32_e32 v63, v219, v63
	v_mul_f32_e32 v64, v219, v64
	v_mul_f32_e32 v65, v219, v65
	v_mul_f32_e32 v58, 0xbfb8aa3b, v58
	v_mul_f32_e32 v59, 0xbfb8aa3b, v59
	s_add_i32 s30, s21, 0xc000
	s_waitcnt lgkmcnt(5)
	v_mfma_f32_32x32x16_bf16 v[146:161], v[162:165], v[174:177], v[146:161]
	v_mul_f32_e32 v60, 0xbfb8aa3b, v60
	v_mul_f32_e32 v61, 0xbfb8aa3b, v61
	v_mul_f32_e32 v62, 0xbfb8aa3b, v62
	v_mul_f32_e32 v63, 0xbfb8aa3b, v63
	v_mul_f32_e32 v64, 0xbfb8aa3b, v64
	v_mul_f32_e32 v65, 0xbfb8aa3b, v65
	s_cmp_eq_u32 s30, 0x24000
	s_waitcnt lgkmcnt(4)
	v_mfma_f32_32x32x16_bf16 v[238:253], v[166:169], v[170:173], v[238:253]
	v_exp_f32_e32 v58, v58
	v_exp_f32_e32 v59, v59
	v_exp_f32_e32 v60, v60
	v_exp_f32_e32 v61, v61
	v_exp_f32_e32 v62, v62
	v_exp_f32_e32 v63, v63
	s_cselect_b32 s30, 0, s30
	v_mfma_f32_32x32x16_bf16 v[202:217], v[166:169], v[174:177], v[202:217]
	v_exp_f32_e32 v64, v64
	v_exp_f32_e32 v65, v65
	v_add_f32_e32 v58, 1.0, v58
	v_add_f32_e32 v59, 1.0, v59
	v_add_f32_e32 v60, 1.0, v60
	v_add_f32_e32 v61, 1.0, v61
	s_sub_i32 s23, s30, s21
	s_mov_b32 s21, s30
	ds_read_b128 v[162:165], v180
	ds_read_b128 v[170:173], v233
	ds_read_b128 v[174:177], v233 offset:4096
	ds_read_b128 v[166:169], v180 offset:4096
	s_waitcnt lgkmcnt(6)
	v_mfma_f32_32x32x16_bf16 v[130:145], v[186:189], v[194:197], v[130:145]
	v_add_f32_e32 v62, 1.0, v62
	v_add_f32_e32 v63, 1.0, v63
	v_add_f32_e32 v64, 1.0, v64
	v_add_f32_e32 v65, 1.0, v65
	v_rcp_f32_e32 v58, v58
	v_rcp_f32_e32 v59, v59
	v_add_u32_e32 v230, s23, v230
	v_add_u32_e32 v234, s23, v234
	s_waitcnt lgkmcnt(5)
	v_mfma_f32_32x32x16_bf16 v[146:161], v[186:189], v[198:201], v[146:161]
	v_rcp_f32_e32 v60, v60
	v_rcp_f32_e32 v61, v61
	v_rcp_f32_e32 v62, v62
	v_rcp_f32_e32 v63, v63
	v_rcp_f32_e32 v64, v64
	v_rcp_f32_e32 v65, v65
	v_add_u32_e32 v231, s23, v231
	v_add_u32_e32 v235, s23, v235
	s_waitcnt lgkmcnt(4)
	v_mfma_f32_32x32x16_bf16 v[238:253], v[190:193], v[194:197], v[238:253]
	v_cvt_pk_bf16_f32 v54, v58, v59
	v_cvt_pk_bf16_f32 v55, v60, v61
	v_cvt_pk_bf16_f32 v56, v62, v63
	v_cvt_pk_bf16_f32 v57, v64, v65
	v_add_u32_e32 v232, s23, v232
	v_add_u32_e32 v237, s23, v237
	v_mfma_f32_32x32x16_bf16 v[202:217], v[190:193], v[198:201], v[202:217]
	v_add_u32_e32 v233, s23, v233
	v_add_u32_e32 v180, s23, v180
	s_waitcnt lgkmcnt(0)
	v_mfma_f32_32x32x16_bf16 v[130:145], v[162:165], v[170:173], v[130:145]
	v_mfma_f32_32x32x16_bf16 v[146:161], v[162:165], v[174:177], v[146:161]
	v_mfma_f32_32x32x16_bf16 v[238:253], v[166:169], v[170:173], v[238:253]
	v_mfma_f32_32x32x16_bf16 v[202:217], v[166:169], v[174:177], v[202:217]
	s_nop 15
	v_lshlrev_b32_e32 v220, 16, v2
	v_and_b32_e32 v221, 0xffff0000, v2
	v_pk_fma_f32 v[66:67], v[130:131], v[220:221], v[66:67]
	v_lshlrev_b32_e32 v222, 16, v3
	v_and_b32_e32 v223, 0xffff0000, v3
	v_pk_fma_f32 v[68:69], v[132:133], v[222:223], v[68:69]
	v_lshlrev_b32_e32 v220, 16, v4
	v_and_b32_e32 v221, 0xffff0000, v4
	v_pk_fma_f32 v[70:71], v[134:135], v[220:221], v[70:71]
	v_lshlrev_b32_e32 v222, 16, v5
	v_and_b32_e32 v223, 0xffff0000, v5
	v_pk_fma_f32 v[72:73], v[136:137], v[222:223], v[72:73]
	v_lshlrev_b32_e32 v220, 16, v6
	v_and_b32_e32 v221, 0xffff0000, v6
	v_pk_fma_f32 v[74:75], v[138:139], v[220:221], v[74:75]
	v_lshlrev_b32_e32 v222, 16, v7
	v_and_b32_e32 v223, 0xffff0000, v7
	v_pk_fma_f32 v[76:77], v[140:141], v[222:223], v[76:77]
	v_lshlrev_b32_e32 v220, 16, v8
	v_and_b32_e32 v221, 0xffff0000, v8
	v_pk_fma_f32 v[78:79], v[142:143], v[220:221], v[78:79]
	v_lshlrev_b32_e32 v222, 16, v9
	v_and_b32_e32 v223, 0xffff0000, v9
	v_pk_fma_f32 v[80:81], v[144:145], v[222:223], v[80:81]
	v_lshlrev_b32_e32 v220, 16, v18
	v_and_b32_e32 v221, 0xffff0000, v18
	v_pk_fma_f32 v[82:83], v[146:147], v[220:221], v[82:83]
	v_lshlrev_b32_e32 v222, 16, v19
	v_and_b32_e32 v223, 0xffff0000, v19
	v_pk_fma_f32 v[84:85], v[148:149], v[222:223], v[84:85]
	v_lshlrev_b32_e32 v220, 16, v20
	v_and_b32_e32 v221, 0xffff0000, v20
	v_pk_fma_f32 v[86:87], v[150:151], v[220:221], v[86:87]
	v_lshlrev_b32_e32 v222, 16, v21
	v_and_b32_e32 v223, 0xffff0000, v21
	v_pk_fma_f32 v[88:89], v[152:153], v[222:223], v[88:89]
	v_lshlrev_b32_e32 v220, 16, v22
	v_and_b32_e32 v221, 0xffff0000, v22
	v_pk_fma_f32 v[90:91], v[154:155], v[220:221], v[90:91]
	v_lshlrev_b32_e32 v222, 16, v23
	v_and_b32_e32 v223, 0xffff0000, v23
	v_pk_fma_f32 v[92:93], v[156:157], v[222:223], v[92:93]
	v_lshlrev_b32_e32 v220, 16, v24
	v_and_b32_e32 v221, 0xffff0000, v24
	v_pk_fma_f32 v[94:95], v[158:159], v[220:221], v[94:95]
	v_lshlrev_b32_e32 v222, 16, v25
	v_and_b32_e32 v223, 0xffff0000, v25
	v_pk_fma_f32 v[96:97], v[160:161], v[222:223], v[96:97]
	v_lshlrev_b32_e32 v220, 16, v34
	v_and_b32_e32 v221, 0xffff0000, v34
	v_pk_fma_f32 v[98:99], v[238:239], v[220:221], v[98:99]
	v_lshlrev_b32_e32 v222, 16, v35
	v_and_b32_e32 v223, 0xffff0000, v35
	v_pk_fma_f32 v[100:101], v[240:241], v[222:223], v[100:101]
	v_lshlrev_b32_e32 v220, 16, v36
	v_and_b32_e32 v221, 0xffff0000, v36
	v_pk_fma_f32 v[102:103], v[242:243], v[220:221], v[102:103]
	v_lshlrev_b32_e32 v222, 16, v37
	v_and_b32_e32 v223, 0xffff0000, v37
	v_pk_fma_f32 v[104:105], v[244:245], v[222:223], v[104:105]
	v_lshlrev_b32_e32 v220, 16, v38
	v_and_b32_e32 v221, 0xffff0000, v38
	v_pk_fma_f32 v[106:107], v[246:247], v[220:221], v[106:107]
	v_lshlrev_b32_e32 v222, 16, v39
	v_and_b32_e32 v223, 0xffff0000, v39
	v_pk_fma_f32 v[108:109], v[248:249], v[222:223], v[108:109]
	v_lshlrev_b32_e32 v220, 16, v40
	v_and_b32_e32 v221, 0xffff0000, v40
	v_pk_fma_f32 v[110:111], v[250:251], v[220:221], v[110:111]
	v_lshlrev_b32_e32 v222, 16, v41
	v_and_b32_e32 v223, 0xffff0000, v41
	v_pk_fma_f32 v[112:113], v[252:253], v[222:223], v[112:113]
	v_lshlrev_b32_e32 v220, 16, v50
	v_and_b32_e32 v221, 0xffff0000, v50
	v_pk_fma_f32 v[114:115], v[202:203], v[220:221], v[114:115]
	v_lshlrev_b32_e32 v222, 16, v51
	v_and_b32_e32 v223, 0xffff0000, v51
	v_pk_fma_f32 v[116:117], v[204:205], v[222:223], v[116:117]
	v_lshlrev_b32_e32 v220, 16, v52
	v_and_b32_e32 v221, 0xffff0000, v52
	v_pk_fma_f32 v[118:119], v[206:207], v[220:221], v[118:119]
	v_lshlrev_b32_e32 v222, 16, v53
	v_and_b32_e32 v223, 0xffff0000, v53
	v_pk_fma_f32 v[120:121], v[208:209], v[222:223], v[120:121]
	v_lshlrev_b32_e32 v220, 16, v54
	v_and_b32_e32 v221, 0xffff0000, v54
	v_pk_fma_f32 v[122:123], v[210:211], v[220:221], v[122:123]
	v_lshlrev_b32_e32 v222, 16, v55
	v_and_b32_e32 v223, 0xffff0000, v55
	v_pk_fma_f32 v[124:125], v[212:213], v[222:223], v[124:125]
	v_lshlrev_b32_e32 v220, 16, v56
	v_and_b32_e32 v221, 0xffff0000, v56
	v_pk_fma_f32 v[126:127], v[214:215], v[220:221], v[126:127]
	v_lshlrev_b32_e32 v222, 16, v57
	v_and_b32_e32 v223, 0xffff0000, v57
	v_pk_fma_f32 v[128:129], v[216:217], v[222:223], v[128:129]
	s_add_i32 s26, s26, 1
	s_cmp_lg_u32 s26, 4
	s_cbranch_scc1 .Lmg_iloop
	v_cvt_pk_bf16_f32 v220, v66, v67
	v_cvt_pk_bf16_f32 v221, v68, v69
	global_store_dwordx2 v178, v[220:221], s[42:43] offset:0
	v_cvt_pk_bf16_f32 v222, v70, v71
	v_cvt_pk_bf16_f32 v223, v72, v73
	global_store_dwordx2 v178, v[222:223], s[42:43] offset:16
	v_cvt_pk_bf16_f32 v220, v74, v75
	v_cvt_pk_bf16_f32 v221, v76, v77
	global_store_dwordx2 v178, v[220:221], s[42:43] offset:32
	v_cvt_pk_bf16_f32 v222, v78, v79
	v_cvt_pk_bf16_f32 v223, v80, v81
	global_store_dwordx2 v178, v[222:223], s[42:43] offset:48
	v_cvt_pk_bf16_f32 v220, v82, v83
	v_cvt_pk_bf16_f32 v221, v84, v85
	global_store_dwordx2 v179, v[220:221], s[42:43] offset:0
	v_cvt_pk_bf16_f32 v222, v86, v87
	v_cvt_pk_bf16_f32 v223, v88, v89
	global_store_dwordx2 v179, v[222:223], s[42:43] offset:16
	v_cvt_pk_bf16_f32 v220, v90, v91
	v_cvt_pk_bf16_f32 v221, v92, v93
	global_store_dwordx2 v179, v[220:221], s[42:43] offset:32
	v_cvt_pk_bf16_f32 v222, v94, v95
	v_cvt_pk_bf16_f32 v223, v96, v97
	global_store_dwordx2 v179, v[222:223], s[42:43] offset:48
	v_cvt_pk_bf16_f32 v220, v98, v99
	v_cvt_pk_bf16_f32 v221, v100, v101
	global_store_dwordx2 v178, v[220:221], s[42:43] offset:64
	v_cvt_pk_bf16_f32 v222, v102, v103
	v_cvt_pk_bf16_f32 v223, v104, v105
	global_store_dwordx2 v178, v[222:223], s[42:43] offset:80
	v_cvt_pk_bf16_f32 v220, v106, v107
	v_cvt_pk_bf16_f32 v221, v108, v109
	global_store_dwordx2 v178, v[220:221], s[42:43] offset:96
	v_cvt_pk_bf16_f32 v222, v110, v111
	v_cvt_pk_bf16_f32 v223, v112, v113
	global_store_dwordx2 v178, v[222:223], s[42:43] offset:112
	v_cvt_pk_bf16_f32 v220, v114, v115
	v_cvt_pk_bf16_f32 v221, v116, v117
	global_store_dwordx2 v179, v[220:221], s[42:43] offset:64
	v_cvt_pk_bf16_f32 v222, v118, v119
	v_cvt_pk_bf16_f32 v223, v120, v121
	global_store_dwordx2 v179, v[222:223], s[42:43] offset:80
	v_cvt_pk_bf16_f32 v220, v122, v123
	v_cvt_pk_bf16_f32 v221, v124, v125
	global_store_dwordx2 v179, v[220:221], s[42:43] offset:96
	v_cvt_pk_bf16_f32 v222, v126, v127
	v_cvt_pk_bf16_f32 v223, v128, v129
	global_store_dwordx2 v179, v[222:223], s[42:43] offset:112
	s_waitcnt vmcnt(0)
	s_barrier
	s_add_i32 s24, s24, s84
	s_cmpk_gt_i32 s24, 0x1ff
	s_cbranch_scc0 .Lmg_unit
